# phase-3 latent rmsnorm loop: gain vectors loaded once before the loop, four rows reduced together with DPP/permlane adds (replaces serial bpermute chains + dependent per-row gain load)
# speedup vs baseline: 1.0011x; 1.0011x over previous
.Lln_std:
	v_cmp_gt_i32_e32 vcc, s25, v2
	s_and_saveexec_b64 s[12:13], vcc
	v_readlane_b32 s96, v254, 21
	v_readlane_b32 s97, v254, 22
	s_mov_b32 s2, s26
	v_readlane_b32 s3, v254, 24
	s_cbranch_execz .LBB0_1583
	v_and_b32_e32 v1, 64, v194
	v_add_u32_e32 v3, 64, v1
	v_xor_b32_e32 v1, 32, v194
	v_cmp_lt_i32_e32 vcc, v1, v3
	v_xor_b32_e32 v4, 16, v194
	v_and_b32_e32 v0, 63, v163
	v_cndmask_b32_e32 v1, v194, v1, vcc
	v_cmp_lt_i32_e32 vcc, v4, v3
	v_readlane_b32 s0, v254, 30
	v_lshlrev_b32_e32 v0, 2, v0
	v_cndmask_b32_e32 v4, v194, v4, vcc
	v_lshlrev_b32_e32 v16, 2, v4
	v_xor_b32_e32 v4, 8, v194
	v_cmp_lt_i32_e32 vcc, v4, v3
	s_lshl_b32 s14, s0, 8
	s_mov_b32 s15, s77
	v_cndmask_b32_e32 v4, v194, v4, vcc
	v_lshlrev_b32_e32 v17, 2, v4
	v_xor_b32_e32 v4, 4, v194
	v_cmp_lt_i32_e32 vcc, v4, v3
	v_lshlrev_b32_e32 v1, 2, v1
	s_mov_b64 s[18:19], 0
	v_cndmask_b32_e32 v4, v194, v4, vcc
	v_lshlrev_b32_e32 v18, 2, v4
	v_xor_b32_e32 v4, 2, v194
	v_cmp_lt_i32_e32 vcc, v4, v3
	v_readlane_b32 s1, v254, 31
	s_nop 0
	v_cndmask_b32_e32 v4, v194, v4, vcc
	v_lshlrev_b32_e32 v19, 2, v4
	v_xor_b32_e32 v4, 1, v194
	v_cmp_lt_i32_e32 vcc, v4, v3
	s_nop 1
	v_cndmask_b32_e32 v3, v194, v4, vcc
	v_lshlrev_b32_e32 v20, 2, v3
	v_lshlrev_b32_e32 v206, 2, v0
	s_lshl_b64 s[28:29], s[14:15], 2
	s_add_u32 s30, s60, s28
	s_addc_u32 s31, s61, s29
	global_load_dwordx4 v[200:203], v206, s[30:31]
	s_add_u32 s30, s64, s28
	s_addc_u32 s31, s65, s29
	global_load_dwordx4 v[242:245], v206, s[30:31]
	s_branch .LBB0_1577

.LBB0_1577:
	v_cmp_lt_i32_e64 s[0:1], s34, v2
	v_add_u32_e32 v3, 0xffffc000, v2
	v_mov_b32_e32 v24, 0x8800000
	v_cndmask_b32_e64 v4, v2, v3, s[0:1]
	v_mov_b32_e32 v25, 0x9000000
	v_cndmask_b32_e64 v160, v24, v25, s[0:1]
	v_ashrrev_i32_e32 v5, 31, v4
	v_lshl_add_u64 v[6:7], s[16:17], 0, v[160:161]
	v_lshlrev_b64 v[4:5], 9, v[4:5]
	v_lshl_add_u64 v[4:5], v[6:7], 0, v[4:5]
	v_lshlrev_b32_e32 v160, 1, v0
	s_waitcnt vmcnt(0)
	v_lshl_add_u64 v[14:15], v[4:5], 0, v[160:161]
	global_load_dwordx2 v[22:23], v[14:15], off
	v_add_u32_e32 v3, s2, v2
	v_cmp_gt_i32_e64 s[10:11], s25, v3
	v_mov_b32_e32 v7, v161
	v_mov_b32_e32 v30, s64
	v_cndmask_b32_e64 v4, v2, v3, s[10:11]
	v_cmp_lt_i32_e64 s[8:9], s34, v4
	v_add_u32_e32 v5, 0xffffc000, v4
	v_add_u32_e32 v3, s2, v3
	v_cndmask_b32_e64 v4, v4, v5, s[8:9]
	v_cndmask_b32_e64 v6, v24, v25, s[8:9]
	v_ashrrev_i32_e32 v5, 31, v4
	v_lshl_add_u64 v[6:7], s[16:17], 0, v[6:7]
	v_lshlrev_b64 v[4:5], 9, v[4:5]
	v_lshl_add_u64 v[4:5], v[6:7], 0, v[4:5]
	v_cmp_gt_i32_e64 s[6:7], s25, v3
	s_waitcnt lgkmcnt(0)
	v_lshl_add_u64 v[8:9], v[4:5], 0, v[160:161]
	v_add_u32_e32 v21, s2, v3
	v_cndmask_b32_e64 v4, v2, v3, s[6:7]
	v_cmp_lt_i32_e64 s[4:5], s34, v4
	v_add_u32_e32 v5, 0xffffc000, v4
	v_cmp_gt_i32_e64 s[2:3], s25, v21
	v_cndmask_b32_e64 v4, v4, v5, s[4:5]
	v_cndmask_b32_e64 v6, v24, v25, s[4:5]
	v_mov_b32_e32 v7, v161
	v_ashrrev_i32_e32 v5, 31, v4
	v_cndmask_b32_e64 v2, v2, v21, s[2:3]
	v_lshl_add_u64 v[6:7], s[16:17], 0, v[6:7]
	v_lshlrev_b64 v[4:5], 9, v[4:5]
	v_cmp_lt_i32_e32 vcc, s34, v2
	v_lshl_add_u64 v[4:5], v[6:7], 0, v[4:5]
	v_add_u32_e32 v3, 0xffffc000, v2
	v_cndmask_b32_e32 v6, v24, v25, vcc
	v_cndmask_b32_e32 v2, v2, v3, vcc
	v_mov_b32_e32 v7, v161
	v_ashrrev_i32_e32 v3, 31, v2
	v_lshl_add_u64 v[6:7], s[16:17], 0, v[6:7]
	v_lshlrev_b64 v[2:3], 9, v[2:3]
	v_lshl_add_u64 v[2:3], v[6:7], 0, v[2:3]
	v_lshl_add_u64 v[4:5], v[4:5], 0, v[160:161]
	v_lshl_add_u64 v[2:3], v[2:3], 0, v[160:161]
	v_lshlrev_b32_e32 v160, 2, v0
	global_load_dwordx2 v[12:13], v[8:9], off
	global_load_dwordx2 v[10:11], v[4:5], off
	global_load_dwordx2 v[6:7], v[2:3], off
	s_waitcnt vmcnt(0)
	v_lshlrev_b32_e32 v26, 16, v23
	v_and_b32_e32 v27, 0xffff0000, v23
	v_lshlrev_b32_e32 v24, 16, v22
	v_and_b32_e32 v25, 0xffff0000, v22
	v_lshlrev_b32_e32 v29, 16, v13
	v_and_b32_e32 v30, 0xffff0000, v13
	v_lshlrev_b32_e32 v188, 16, v12
	v_and_b32_e32 v189, 0xffff0000, v12
	v_lshlrev_b32_e32 v193, 16, v11
	v_and_b32_e32 v241, 0xffff0000, v11
	v_lshlrev_b32_e32 v246, 16, v10
	v_and_b32_e32 v247, 0xffff0000, v10
	v_lshlrev_b32_e32 v249, 16, v7
	v_and_b32_e32 v250, 0xffff0000, v7
	v_lshlrev_b32_e32 v22, 16, v6
	v_and_b32_e32 v23, 0xffff0000, v6
	v_mul_f32_e32 v28, v24, v24
	v_mul_f32_e32 v185, v188, v188
	v_mul_f32_e32 v248, v246, v246
	v_mul_f32_e32 v206, v22, v22
	v_fmac_f32_e32 v28, v25, v25
	v_fmac_f32_e32 v185, v189, v189
	v_fmac_f32_e32 v248, v247, v247
	v_fmac_f32_e32 v206, v23, v23
	v_fmac_f32_e32 v28, v26, v26
	v_fmac_f32_e32 v185, v29, v29
	v_fmac_f32_e32 v248, v193, v193
	v_fmac_f32_e32 v206, v249, v249
	v_fmac_f32_e32 v28, v27, v27
	v_fmac_f32_e32 v185, v30, v30
	v_fmac_f32_e32 v248, v241, v241
	v_fmac_f32_e32 v206, v250, v250
	s_nop 1
	v_add_f32_dpp v28, v28, v28 quad_perm:[1,0,3,2] row_mask:0xf bank_mask:0xf
	v_add_f32_dpp v185, v185, v185 quad_perm:[1,0,3,2] row_mask:0xf bank_mask:0xf
	v_add_f32_dpp v248, v248, v248 quad_perm:[1,0,3,2] row_mask:0xf bank_mask:0xf
	v_add_f32_dpp v206, v206, v206 quad_perm:[1,0,3,2] row_mask:0xf bank_mask:0xf
	s_nop 1
	v_add_f32_dpp v28, v28, v28 quad_perm:[2,3,0,1] row_mask:0xf bank_mask:0xf
	v_add_f32_dpp v185, v185, v185 quad_perm:[2,3,0,1] row_mask:0xf bank_mask:0xf
	v_add_f32_dpp v248, v248, v248 quad_perm:[2,3,0,1] row_mask:0xf bank_mask:0xf
	v_add_f32_dpp v206, v206, v206 quad_perm:[2,3,0,1] row_mask:0xf bank_mask:0xf
	s_nop 1
	v_add_f32_dpp v28, v28, v28 row_half_mirror row_mask:0xf bank_mask:0xf
	v_add_f32_dpp v185, v185, v185 row_half_mirror row_mask:0xf bank_mask:0xf
	v_add_f32_dpp v248, v248, v248 row_half_mirror row_mask:0xf bank_mask:0xf
	v_add_f32_dpp v206, v206, v206 row_half_mirror row_mask:0xf bank_mask:0xf
	s_nop 1
	v_add_f32_dpp v28, v28, v28 row_mirror row_mask:0xf bank_mask:0xf
	v_add_f32_dpp v185, v185, v185 row_mirror row_mask:0xf bank_mask:0xf
	v_add_f32_dpp v248, v248, v248 row_mirror row_mask:0xf bank_mask:0xf
	v_add_f32_dpp v206, v206, v206 row_mirror row_mask:0xf bank_mask:0xf
	v_mov_b32_e32 v12, v28
	v_mov_b32_e32 v13, v185
	v_mov_b32_e32 v10, v248
	v_mov_b32_e32 v11, v206
	s_nop 1
	v_permlane16_swap_b32_e32 v28, v12
	v_permlane16_swap_b32_e32 v185, v13
	v_permlane16_swap_b32_e32 v248, v10
	v_permlane16_swap_b32_e32 v206, v11
	s_nop 1
	v_add_f32_e32 v28, v28, v12
	v_add_f32_e32 v185, v185, v13
	v_add_f32_e32 v248, v248, v10
	v_add_f32_e32 v206, v206, v11
	v_mov_b32_e32 v12, v28
	v_mov_b32_e32 v13, v185
	v_mov_b32_e32 v10, v248
	v_mov_b32_e32 v11, v206
	s_nop 1
	v_permlane32_swap_b32_e32 v28, v12
	v_permlane32_swap_b32_e32 v185, v13
	v_permlane32_swap_b32_e32 v248, v10
	v_permlane32_swap_b32_e32 v206, v11
	s_nop 1
	v_add_f32_e32 v28, v28, v12
	v_add_f32_e32 v185, v185, v13
	v_add_f32_e32 v248, v248, v10
	v_add_f32_e32 v206, v206, v11
	v_fmamk_f32 v28, v28, 0x3b800000, v187
	v_fmamk_f32 v185, v185, 0x3b800000, v187
	v_fmamk_f32 v248, v248, 0x3b800000, v187
	v_fmamk_f32 v206, v206, 0x3b800000, v187
	v_rsq_f32_e32 v28, v28
	v_rsq_f32_e32 v185, v185
	v_rsq_f32_e32 v248, v248
	v_rsq_f32_e32 v206, v206
	s_nop 0
	v_cndmask_b32_e64 v12, v200, v242, s[0:1]
	v_cndmask_b32_e64 v13, v201, v243, s[0:1]
	v_cndmask_b32_e64 v10, v202, v244, s[0:1]
	v_cndmask_b32_e64 v11, v203, v245, s[0:1]
	v_mul_f32_e32 v24, v28, v24
	v_mul_f32_e32 v25, v28, v25
	v_mul_f32_e32 v26, v28, v26
	v_mul_f32_e32 v27, v28, v27
	v_mul_f32_e32 v24, v24, v12
	v_mul_f32_e32 v25, v25, v13
	v_mul_f32_e32 v26, v26, v10
	v_mul_f32_e32 v27, v27, v11
	v_cvt_pk_bf16_f32 v24, v24, v25
	v_cvt_pk_bf16_f32 v25, v26, v27
	global_store_dwordx2 v[14:15], v[24:25], off
	v_cndmask_b32_e64 v12, v200, v242, s[8:9]
	v_cndmask_b32_e64 v13, v201, v243, s[8:9]
	v_cndmask_b32_e64 v10, v202, v244, s[8:9]
	v_cndmask_b32_e64 v11, v203, v245, s[8:9]
	v_mul_f32_e32 v188, v185, v188
	v_mul_f32_e32 v189, v185, v189
	v_mul_f32_e32 v29, v185, v29
	v_mul_f32_e32 v30, v185, v30
	v_mul_f32_e32 v188, v188, v12
	v_mul_f32_e32 v189, v189, v13
	v_mul_f32_e32 v29, v29, v10
	v_mul_f32_e32 v30, v30, v11
	v_cvt_pk_bf16_f32 v188, v188, v189
	v_cvt_pk_bf16_f32 v189, v29, v30
	s_and_saveexec_b64 s[20:21], s[10:11]
	global_store_dwordx2 v[8:9], v[188:189], off
	s_or_b64 exec, exec, s[20:21]
	v_cndmask_b32_e64 v12, v200, v242, s[4:5]
	v_cndmask_b32_e64 v13, v201, v243, s[4:5]
	v_cndmask_b32_e64 v10, v202, v244, s[4:5]
	v_cndmask_b32_e64 v11, v203, v245, s[4:5]
	v_mul_f32_e32 v246, v248, v246
	v_mul_f32_e32 v247, v248, v247
	v_mul_f32_e32 v193, v248, v193
	v_mul_f32_e32 v241, v248, v241
	v_mul_f32_e32 v246, v246, v12
	v_mul_f32_e32 v247, v247, v13
	v_mul_f32_e32 v193, v193, v10
	v_mul_f32_e32 v241, v241, v11
	v_cvt_pk_bf16_f32 v246, v246, v247
	v_cvt_pk_bf16_f32 v247, v193, v241
	s_and_saveexec_b64 s[20:21], s[6:7]
	global_store_dwordx2 v[4:5], v[246:247], off
	s_or_b64 exec, exec, s[20:21]
	v_cndmask_b32_e32 v12, v200, v242, vcc
	v_cndmask_b32_e32 v13, v201, v243, vcc
	v_cndmask_b32_e32 v10, v202, v244, vcc
	v_cndmask_b32_e32 v11, v203, v245, vcc
	v_mul_f32_e32 v22, v206, v22
	v_mul_f32_e32 v23, v206, v23
	v_mul_f32_e32 v249, v206, v249
	v_mul_f32_e32 v250, v206, v250
	v_mul_f32_e32 v22, v22, v12
	v_mul_f32_e32 v23, v23, v13
	v_mul_f32_e32 v249, v249, v10
	v_mul_f32_e32 v250, v250, v11
	v_cvt_pk_bf16_f32 v22, v22, v23
	v_cvt_pk_bf16_f32 v23, v249, v250
	s_and_saveexec_b64 s[0:1], s[2:3]
	global_store_dwordx2 v[2:3], v[22:23], off
	s_branch .LBB0_1576
